# GEMM unit scheduler: division by the row-group size (always 8 for M=8192) replaced by shift/mask, removing the VALU reciprocal + readfirstlane chain between units (on top of peel0)
# baseline (speedup 1.0000x reference)
;     __host__ __device__ bool next(int i, Unit& u) const {
;         const long L = (long)i * G + c; if (L >= nwg) return false;
;         int wgid = (int)L; { const int q = nwg / NXCD, r = nwg % NXCD, xcd = wgid % NXCD, off = wgid / NXCD; wgid = (xcd < r ? xcd * (q + 1) : r * (q + 1) + (xcd - r) * q) + off; }
;         const int nig = WGM * nN, gid = wgid / nig, fm = gid * WGM, gsz = (nM - fm) < WGM ? (nM - fm) : WGM;
;         u.pm = fm + ((wgid % nig) % gsz); u.pn = (wgid % nig) / gsz; return true;
.LBB0_162:
	s_add_i32 s26, s26, 1
	s_mul_i32 s40, s26, s53
	s_mul_hi_u32 s41, s26, s52
	s_add_i32 s41, s41, s40
	s_mul_i32 s40, s26, s52
	s_add_u32 s74, s40, s2
	s_addc_u32 s75, s41, s3
	v_mov_b64_e32 v[0:1], 0x300
	v_cmp_lt_i64_e64 s[40:41], s[74:75], v[0:1]
	v_mov_b64_e32 v[0:1], 0x2ff
	v_cmp_gt_i64_e32 vcc, s[74:75], v[0:1]
	s_cbranch_vccnz .LBB0_164
	s_ashr_i32 s44, s74, 31
	s_lshr_b32 s44, s44, 29
	s_add_i32 s44, s74, s44
	s_ashr_i32 s45, s44, 3
	s_and_b32 s44, s44, -8
	s_sub_i32 s44, s74, s44
	s_cmp_lt_i32 s44, 0
	s_movk_i32 s46, 0x61
	s_cselect_b32 s46, s46, 0x60
	s_mul_i32 s44, s44, s46
	s_add_i32 s44, s44, s45
	s_mul_hi_i32 s45, s44, 0x2aaaaaab
	s_lshr_b32 s46, s45, 31
	s_ashr_i32 s45, s45, 5
	s_add_i32 s45, s45, s46
	s_lshl_b32 s46, s45, 3
	s_sub_i32 s47, 32, s46
	s_min_i32 s47, s47, 8
	s_mulk_i32 s45, 0xc0
	s_sub_i32 s45, s44, s45
	s_lshr_b32 s44, s45, 3
	s_and_b32 s45, s45, 7
	s_add_i32 s46, s46, s45

;     __host__ __device__ bool next(int i, Unit& u) const {
;     ...
;         int wgid = (int)L; { const int q = nwg / NXCD, r = nwg % NXCD, xcd = wgid % NXCD, off = wgid / NXCD; wgid = (xcd < r ? xcd * (q + 1) : r * (q + 1) + (xcd - r) * q) + off; }
;         const int nig = WGM * nN, gid = wgid / nig, fm = gid * WGM, gsz = (nM - fm) < WGM ? (nM - fm) : WGM;
;         u.pm = fm + ((wgid % nig) % gsz); u.pn = (wgid % nig) / gsz; return true;
.LBB0_212:
	s_ashr_i32 s16, s16, 3
	s_add_i32 s16, s82, s16
	s_ashr_i32 s42, s16, 31
	s_lshr_b32 s42, s42, 26
	s_add_i32 s42, s16, s42
	s_ashr_i32 s43, s42, 6
	s_lshl_b32 s43, s43, 3
	s_sub_i32 s49, 32, s43
	s_min_i32 s68, s49, 8
	s_andn2_b32 s42, s42, 63
	s_sub_i32 s16, s16, s42
	s_lshr_b32 s49, s16, 3
	s_and_b32 s16, s16, 7
	s_add_i32 s16, s43, s16

;     __host__ __device__ bool next(int i, Unit& u) const {
;         const long L = (long)i * G + c; if (L >= nwg) return false;
;         int wgid = (int)L; { const int q = nwg / NXCD, r = nwg % NXCD, xcd = wgid % NXCD, off = wgid / NXCD; wgid = (xcd < r ? xcd * (q + 1) : r * (q + 1) + (xcd - r) * q) + off; }
;         const int nig = WGM * nN, gid = wgid / nig, fm = gid * WGM, gsz = (nM - fm) < WGM ? (nM - fm) : WGM;
;         u.pm = fm + ((wgid % nig) % gsz); u.pn = (wgid % nig) / gsz; return true;
.LBB0_328:
	s_add_i32 s54, s54, 1
	s_mul_i32 s40, s54, s53
	s_mul_hi_u32 s41, s54, s52
	s_add_i32 s41, s41, s40
	s_mul_i32 s40, s54, s52
	s_add_u32 s46, s40, s2
	s_addc_u32 s47, s41, s3
	v_mov_b64_e32 v[0:1], 0x580
	v_cmp_lt_i64_e64 s[40:41], s[46:47], v[0:1]
	v_mov_b64_e32 v[0:1], 0x57f
	v_cmp_gt_i64_e32 vcc, s[46:47], v[0:1]
	s_cbranch_vccnz .LBB0_330
	s_ashr_i32 s42, s46, 31
	s_lshr_b32 s42, s42, 29
	s_add_i32 s42, s46, s42
	s_ashr_i32 s43, s42, 3
	s_and_b32 s42, s42, -8
	s_sub_i32 s42, s46, s42
	s_cmp_lt_i32 s42, 0
	s_movk_i32 s44, 0xb1
	s_cselect_b32 s44, s44, 0xb0
	s_mul_i32 s42, s42, s44
	s_add_i32 s42, s42, s43
	s_mul_hi_i32 s43, s42, 0x2e8ba2e9
	s_lshr_b32 s44, s43, 31
	s_ashr_i32 s43, s43, 6
	s_add_i32 s43, s43, s44
	s_lshl_b32 s44, s43, 3
	s_sub_i32 s45, 32, s44
	s_min_i32 s45, s45, 8
	s_mulk_i32 s43, 0x160
	s_sub_i32 s43, s42, s43
	s_lshr_b32 s42, s43, 3
	s_and_b32 s43, s43, 7
	s_add_i32 s44, s44, s43
